# P6: P@V tiles of prompt block c moved to workgroup c+128 (after it drains the sample-attention queue); workgroups 0-127 publish softmax rows and join the queue earlier
# baseline (speedup 1.0000x reference)
.LBB0_825:
	v_writelane_b32 v227, 0, 1
	s_waitcnt vmcnt(0)
	s_add_u32 s44, s34, 0x28600000
	v_mov_b32_e32 v10, v164
	s_waitcnt vmcnt(0) lgkmcnt(0)
	s_barrier
	s_addc_u32 s45, s35, 0
	s_andn2_b64 vcc, exec, s[8:9]
	v_readfirstlane_b32 s12, v10
	s_cbranch_vccnz .LBB0_841
	s_cmpk_lg_i32 s26, 0x100
	s_cbranch_scc1 .Lp6_pv_entry
	s_and_saveexec_b64 s[98:99], s[16:17]
	s_cbranch_execz .Lp6_pub_done
	buffer_wbl2 sc1
	s_waitcnt vmcnt(0)
	s_lshl_b32 s100, s2, 2
	v_mov_b32_e32 v0, s100
	v_mov_b32_e32 v1, 1
	global_atomic_add v0, v1, s[34:35]
	s_waitcnt vmcnt(0)
.Lp6_pub_done:
	s_or_b64 exec, exec, s[98:99]
	s_branch .LBB0_841
.Lp6_pv_entry:
	v_lshlrev_b32_e32 v0, 4, v10
	v_add_u32_e32 v1, 0x2000, v0
	v_ashrrev_i32_e32 v2, 31, v1
	v_lshrrev_b32_e32 v2, 22, v2
	v_add_u32_e32 v2, v1, v2
	v_ashrrev_i32_e32 v8, 10, v2
	v_mul_i32_i24_e32 v2, 0x400, v8
	v_sub_u32_e32 v1, v1, v2
	v_lshrrev_b32_e32 v2, 4, v1
	v_bitop3_b32 v1, v2, v1, 32 bitop3:0x6c
	v_ashrrev_i32_e32 v2, 31, v1
	v_lshrrev_b32_e32 v2, 26, v2
	v_add_u32_e32 v2, v1, v2
	v_lshlrev_b32_e32 v3, 3, v8
	v_ashrrev_i32_e32 v9, 6, v2
	v_and_b32_e32 v3, -16, v3
	v_add_u32_e32 v3, v9, v3
	v_and_b32_e32 v4, 3, v9
	s_mov_b32 s8, 0x7fffe0
	v_lshrrev_b32_e32 v5, 2, v3
	v_lshlrev_b32_e32 v6, 1, v3
	v_and_b32_e32 v2, 0xc0, v2
	v_and_or_b32 v4, v3, s8, v4
	v_and_b32_e32 v5, 4, v5
	v_and_b32_e32 v6, 24, v6
	v_sub_u32_e32 v1, v1, v2
	v_mov_b32_e32 v2, 1
	v_or3_b32 v4, v4, v5, v6
	v_lshlrev_b32_e32 v5, 5, v8
	v_ashrrev_i16_sdwa v1, v2, sext(v1) dst_sel:DWORD dst_unused:UNUSED_PAD src0_sel:DWORD src1_sel:BYTE_0
	v_and_b32_e32 v5, 32, v5
	v_bfe_i32 v11, v1, 0, 16
	v_add_lshl_u32 v1, v5, v11, 1
	v_lshl_add_u32 v128, v4, 9, v1
	v_lshl_add_u32 v130, v3, 9, v1
	v_bfe_i32 v1, v10, 27, 1
	v_lshrrev_b32_e32 v1, 22, v1
	v_add_u32_e32 v1, v0, v1
	v_and_b32_e32 v1, 0xfffffc00, v1
	v_sub_u32_e32 v0, v0, v1
	v_lshrrev_b32_e32 v1, 4, v0
	v_ashrrev_i32_e32 v3, 31, v10
	v_bitop3_b32 v0, v1, v0, 32 bitop3:0x6c
	v_lshrrev_b32_e32 v3, 26, v3
	v_ashrrev_i32_e32 v1, 31, v0
	v_add_u32_e32 v3, v10, v3
	v_lshrrev_b32_e32 v1, 26, v1
	v_ashrrev_i32_e32 v13, 6, v3
	s_add_u32 s14, s34, 0x27200000
	v_add_u32_e32 v1, v0, v1
	v_lshlrev_b32_e32 v3, 3, v13
	s_addc_u32 s15, s35, 0
	v_ashrrev_i32_e32 v12, 6, v1
	v_and_b32_e32 v3, -16, v3
	s_ashr_i32 s13, s2, 5
	s_bfe_u32 s19, s2, 0x20003
	v_add_u32_e32 v3, v12, v3
	v_and_b32_e32 v4, 3, v12
	s_lshl_b32 s46, s13, 13
	s_lshl_b32 s47, s19, 11
	s_lshl_b32 s9, s2, 8
	v_and_or_b32 v4, v3, s8, v4
	s_or_b32 s8, s47, s46
	s_and_b32 s49, s9, 0x700
	s_or_b32 s8, s8, s49
	s_ashr_i32 s10, s12, 6
	s_ashr_i32 s9, s8, 31
	s_ashr_i32 s11, s12, 8
	s_lshl_b32 s3, s10, 10
	s_lshl_b64 s[8:9], s[8:9], 9
	s_add_u32 s6, s6, s8
	s_addc_u32 s7, s7, s9
	s_lshl_b32 s40, s13, 11
	s_lshl_b32 s48, s19, 9
	v_lshrrev_b32_e32 v5, 2, v3
	v_lshlrev_b32_e32 v6, 1, v3
	v_and_b32_e32 v1, 0xc0, v1
	s_or_b32 s8, s48, s40
	v_and_b32_e32 v5, 4, v5
	v_and_b32_e32 v6, 24, v6
	v_sub_u32_e32 v0, v0, v1
	s_ashr_i32 s9, s8, 31
	v_or3_b32 v4, v4, v5, v6
	v_lshlrev_b32_e32 v5, 5, v13
	v_ashrrev_i16_sdwa v0, v2, sext(v0) dst_sel:DWORD dst_unused:UNUSED_PAD src0_sel:DWORD src1_sel:BYTE_0
	s_lshl_b64 s[8:9], s[8:9], 9
	v_and_b32_e32 v5, 32, v5
	v_bfe_i32 v14, v0, 0, 16
	s_add_u32 s50, s14, s8
	v_add_lshl_u32 v0, v5, v14, 1
	s_addc_u32 s51, s15, s9
	s_add_i32 s19, s3, 0
	v_lshl_add_u32 v132, v4, 9, v0
	s_add_i32 m0, s19, 0x10000
	v_lshl_add_u32 v134, v3, 9, v0
	global_load_lds_dwordx4 v132, s[50:51]
	s_add_i32 m0, s19, 0x12000
	s_add_u32 s8, s50, 0x10000
	global_load_lds_dwordx4 v128, s[50:51]
	s_addc_u32 s9, s51, 0
	s_add_i32 m0, s19, 0x14000
	s_add_i32 s25, s19, 0x2000
	global_load_lds_dwordx4 v132, s[8:9]
	s_add_i32 m0, s19, 0x16000
	v_mov_b32_e32 v133, 0
	global_load_lds_dwordx4 v128, s[8:9]
	s_mov_b32 m0, s19
	s_add_u32 s8, s6, 0x10000
	global_load_lds_dwordx4 v134, s[6:7]
	s_mov_b32 m0, s25
	s_addc_u32 s9, s7, 0
	s_add_i32 s29, s19, 0x4000
	global_load_lds_dwordx4 v130, s[6:7]
	s_mov_b32 m0, s29
	s_add_i32 s58, s19, 0x6000
	global_load_lds_dwordx4 v134, s[8:9]
	s_mov_b32 m0, s58
	v_mov_b32_e32 v129, v133
	global_load_lds_dwordx4 v130, s[8:9]
	v_mov_b32_e32 v135, v133
	v_mov_b32_e32 v131, v133
	s_cmp_eq_u32 s11, 1
	v_lshl_add_u64 v[6:7], s[50:51], 0, v[132:133]
	v_lshl_add_u64 v[4:5], s[50:51], 0, v[128:129]
	v_lshl_add_u64 v[0:1], s[6:7], 0, v[134:135]
	s_cselect_b64 s[8:9], -1, 0
	s_cmp_lg_u32 s11, 1
	v_lshl_add_u64 v[2:3], s[6:7], 0, v[130:131]
	s_cbranch_scc1 .LBB0_828
	s_barrier

.LBB0_840:
	s_waitcnt vmcnt(0)
	s_barrier
	s_cmpk_lg_i32 s26, 0x100
	s_cbranch_scc1 .LBB0_841
	v_readlane_b32 s2, v227, 0
	v_readfirstlane_b32 s96, v164
	v_mov_b32_e32 v144, v164
	s_nop 3

.LBB0_889:
	s_cmpk_lg_i32 s26, 0x100
	s_cbranch_scc1 .Lp6_after_pv
	s_cmpk_lt_u32 s2, 0x80
	s_cbranch_scc1 .Lp6_after_pv
	v_readlane_b32 s100, v227, 1
	s_nop 3
	s_cmp_lg_u32 s100, 0
	s_cbranch_scc1 .Lp6_after_pv
	v_writelane_b32 v227, 1, 1
	s_waitcnt vmcnt(0) lgkmcnt(0)
	s_barrier
	s_and_saveexec_b64 s[98:99], s[16:17]
	s_cbranch_execz .Lp6_wait_done
	s_add_i32 s100, s2, 0xffffff80
	s_lshl_b32 s100, s100, 2
	v_mov_b32_e32 v0, s100
	s_mov_b32 s101, 0
.Lp6_spin:
	global_load_dword v1, v0, s[34:35] sc1
	s_waitcnt vmcnt(0)
	v_cmp_ne_u32_e32 vcc, 0, v1
	s_nop 1
	s_cbranch_vccnz .Lp6_got
	s_sleep 4
	s_add_i32 s101, s101, 1
	s_cmp_lt_u32 s101, 0x100000
	s_cbranch_scc1 .Lp6_spin
.Lp6_got:
	buffer_inv sc1
	s_waitcnt vmcnt(0)
.Lp6_wait_done:
	s_or_b64 exec, exec, s[98:99]
	s_barrier
	v_writelane_b32 v227, s2, 0
	s_add_i32 s2, s2, 0xffffff80
	s_add_u32 s6, s34, 0x27600000
	s_addc_u32 s7, s35, 0
	s_add_u32 s44, s34, 0x28600000
	s_addc_u32 s45, s35, 0
	v_mov_b32_e32 v144, v164
	v_mov_b32_e32 v10, v164
	s_nop 1
	v_readfirstlane_b32 s12, v10
	s_branch .Lp6_pv_entry
